# weight-copy loops (P0, P4): the 8 serialized gain-pair loads of an item (each followed by vmcnt(0)) issued as one batch
# baseline (speedup 1.0000x reference)
.LBB0_39:
	s_cmp_lg_u64 s[8:9], 0
	s_cselect_b64 s[60:61], -1, 0
	s_cmp_eq_u64 s[8:9], 0
	s_barrier
	s_cbranch_scc1 .LBB0_88
	s_lshl_b32 s6, s3, 2
	v_mov_b32_e32 v104, s6
	s_waitcnt lgkmcnt(0)
	global_load_dwordx2 v[146:147], v104, s[8:9]
	global_load_dwordx2 v[148:149], v104, s[8:9] offset:8
	global_load_dwordx2 v[150:151], v104, s[8:9] offset:16
	global_load_dwordx2 v[152:153], v104, s[8:9] offset:24
	global_load_dwordx2 v[154:155], v104, s[8:9] offset:32
	global_load_dwordx2 v[156:157], v104, s[8:9] offset:40
	global_load_dwordx2 v[158:159], v104, s[8:9] offset:48
	global_load_dwordx2 v[160:161], v104, s[8:9] offset:56
	s_waitcnt vmcnt(0)
	v_mov_b32_e32 v108, v146
	v_mov_b32_e32 v109, v147
	v_pk_mul_f32 v[106:107], v[6:7], v[108:109] op_sel_hi:[1,0]
	v_pk_mul_f32 v[104:105], v[4:5], v[108:109] op_sel_hi:[1,0]
	ds_write_b128 v116, v[104:107]
	v_mov_b32_e32 v104, v109
	s_cbranch_execnz .LBB0_42

.LBB0_42:
	s_waitcnt lgkmcnt(0)
	v_cndmask_b32_e64 v108, 0, 1, s[60:61]
	s_waitcnt vmcnt(14)
	v_pk_mul_f32 v[106:107], v[2:3], v[104:105] op_sel_hi:[1,0]
	v_pk_mul_f32 v[104:105], v[0:1], v[104:105] op_sel_hi:[1,0]
	v_cmp_ne_u32_e64 s[6:7], 1, v108
	s_andn2_b64 vcc, exec, s[60:61]
	ds_write_b128 v117, v[104:107]
	s_cbranch_vccnz .LBB0_89
	s_lshl_b32 s60, s3, 2
	v_mov_b32_e32 v104, s60
	v_mov_b32_e32 v108, v148
	v_mov_b32_e32 v109, v149
	v_pk_mul_f32 v[106:107], v[10:11], v[108:109] op_sel_hi:[1,0]
	v_pk_mul_f32 v[104:105], v[8:9], v[108:109] op_sel_hi:[1,0]
	ds_write_b128 v118, v[104:107]
	v_mov_b32_e32 v104, v109
	s_cbranch_execnz .LBB0_45

.LBB0_45:
	s_waitcnt vmcnt(12)
	v_pk_mul_f32 v[106:107], v[14:15], v[104:105] op_sel_hi:[1,0]
	v_pk_mul_f32 v[104:105], v[12:13], v[104:105] op_sel_hi:[1,0]
	s_and_b64 vcc, exec, s[6:7]
	ds_write_b128 v119, v[104:107]
	s_cbranch_vccnz .LBB0_90
	s_lshl_b32 s60, s3, 2
	v_mov_b32_e32 v104, s60
	v_mov_b32_e32 v108, v150
	v_mov_b32_e32 v109, v151
	v_pk_mul_f32 v[106:107], v[18:19], v[108:109] op_sel_hi:[1,0]
	v_pk_mul_f32 v[104:105], v[16:17], v[108:109] op_sel_hi:[1,0]
	ds_write_b128 v120, v[104:107]
	v_mov_b32_e32 v104, v109
	s_cbranch_execnz .LBB0_48

.LBB0_48:
	s_waitcnt vmcnt(10)
	v_pk_mul_f32 v[106:107], v[22:23], v[104:105] op_sel_hi:[1,0]
	v_pk_mul_f32 v[104:105], v[20:21], v[104:105] op_sel_hi:[1,0]
	s_and_b64 vcc, exec, s[6:7]
	ds_write_b128 v121, v[104:107]
	s_cbranch_vccnz .LBB0_91
	s_lshl_b32 s60, s3, 2
	v_mov_b32_e32 v104, s60
	v_mov_b32_e32 v108, v152
	v_mov_b32_e32 v109, v153
	v_pk_mul_f32 v[106:107], v[26:27], v[108:109] op_sel_hi:[1,0]
	v_pk_mul_f32 v[104:105], v[24:25], v[108:109] op_sel_hi:[1,0]
	ds_write_b128 v122, v[104:107]
	v_mov_b32_e32 v104, v109
	s_cbranch_execnz .LBB0_51

.LBB0_51:
	s_waitcnt vmcnt(8)
	v_pk_mul_f32 v[106:107], v[30:31], v[104:105] op_sel_hi:[1,0]
	v_pk_mul_f32 v[104:105], v[28:29], v[104:105] op_sel_hi:[1,0]
	s_and_b64 vcc, exec, s[6:7]
	ds_write_b128 v123, v[104:107]
	s_cbranch_vccnz .LBB0_92
	s_lshl_b32 s60, s3, 2
	v_mov_b32_e32 v104, s60
	v_mov_b32_e32 v108, v154
	v_mov_b32_e32 v109, v155
	v_pk_mul_f32 v[106:107], v[34:35], v[108:109] op_sel_hi:[1,0]
	v_pk_mul_f32 v[104:105], v[32:33], v[108:109] op_sel_hi:[1,0]
	ds_write_b128 v124, v[104:107]
	v_mov_b32_e32 v104, v109
	s_cbranch_execnz .LBB0_54

.LBB0_54:
	s_waitcnt vmcnt(6)
	v_pk_mul_f32 v[106:107], v[38:39], v[104:105] op_sel_hi:[1,0]
	v_pk_mul_f32 v[104:105], v[36:37], v[104:105] op_sel_hi:[1,0]
	s_and_b64 vcc, exec, s[6:7]
	ds_write_b128 v125, v[104:107]
	s_cbranch_vccnz .LBB0_93
	s_lshl_b32 s60, s3, 2
	v_mov_b32_e32 v104, s60
	v_mov_b32_e32 v108, v156
	v_mov_b32_e32 v109, v157
	v_pk_mul_f32 v[106:107], v[42:43], v[108:109] op_sel_hi:[1,0]
	v_pk_mul_f32 v[104:105], v[40:41], v[108:109] op_sel_hi:[1,0]
	ds_write_b128 v126, v[104:107]
	v_mov_b32_e32 v104, v109
	s_cbranch_execnz .LBB0_57

.LBB0_57:
	s_waitcnt vmcnt(4)
	v_pk_mul_f32 v[106:107], v[46:47], v[104:105] op_sel_hi:[1,0]
	v_pk_mul_f32 v[104:105], v[44:45], v[104:105] op_sel_hi:[1,0]
	s_and_b64 vcc, exec, s[6:7]
	ds_write_b128 v127, v[104:107]
	s_cbranch_vccnz .LBB0_94
	s_lshl_b32 s60, s3, 2
	v_mov_b32_e32 v104, s60
	v_mov_b32_e32 v108, v158
	v_mov_b32_e32 v109, v159
	v_pk_mul_f32 v[106:107], v[50:51], v[108:109] op_sel_hi:[1,0]
	v_pk_mul_f32 v[104:105], v[48:49], v[108:109] op_sel_hi:[1,0]
	ds_write_b128 v128, v[104:107]
	v_mov_b32_e32 v104, v109
	s_cbranch_execnz .LBB0_60

.LBB0_60:
	s_waitcnt vmcnt(2)
	v_pk_mul_f32 v[106:107], v[54:55], v[104:105] op_sel_hi:[1,0]
	v_pk_mul_f32 v[104:105], v[52:53], v[104:105] op_sel_hi:[1,0]
	s_and_b64 vcc, exec, s[6:7]
	ds_write_b128 v129, v[104:107]
	s_cbranch_vccnz .LBB0_95
	s_lshl_b32 s6, s3, 2
	v_mov_b32_e32 v104, s6
	v_mov_b32_e32 v108, v160
	v_mov_b32_e32 v109, v161
	v_pk_mul_f32 v[106:107], v[58:59], v[108:109] op_sel_hi:[1,0]
	v_pk_mul_f32 v[104:105], v[56:57], v[108:109] op_sel_hi:[1,0]
	ds_write_b128 v130, v[104:107]
	v_mov_b32_e32 v104, v109
	s_cbranch_execnz .LBB0_63

.LBB0_609:
	s_cmp_lg_u64 s[6:7], 0
	s_cselect_b64 s[44:45], -1, 0
	s_cmp_eq_u64 s[6:7], 0
	s_barrier
	s_cbranch_scc1 .LBB0_658
	s_lshl_b32 s4, s60, 2
	v_mov_b32_e32 v106, s4
	s_waitcnt lgkmcnt(0)
	global_load_dwordx2 v[150:151], v106, s[6:7]
	global_load_dwordx2 v[152:153], v106, s[6:7] offset:8
	global_load_dwordx2 v[154:155], v106, s[6:7] offset:16
	global_load_dwordx2 v[156:157], v106, s[6:7] offset:24
	global_load_dwordx2 v[158:159], v106, s[6:7] offset:32
	global_load_dwordx2 v[160:161], v106, s[6:7] offset:40
	global_load_dwordx2 v[162:163], v106, s[6:7] offset:48
	global_load_dwordx2 v[164:165], v106, s[6:7] offset:56
	s_waitcnt vmcnt(0)
	v_mov_b32_e32 v110, v150
	v_mov_b32_e32 v111, v151
	v_pk_mul_f32 v[108:109], v[2:3], v[110:111] op_sel_hi:[1,0]
	v_pk_mul_f32 v[106:107], v[0:1], v[110:111] op_sel_hi:[1,0]
	ds_write_b128 v65, v[106:109]
	v_mov_b32_e32 v106, v111
	s_cbranch_execnz .LBB0_612

.LBB0_612:
	s_waitcnt lgkmcnt(0)
	v_cndmask_b32_e64 v110, 0, 1, s[44:45]
	s_waitcnt vmcnt(14)
	v_pk_mul_f32 v[108:109], v[6:7], v[106:107] op_sel_hi:[1,0]
	v_pk_mul_f32 v[106:107], v[4:5], v[106:107] op_sel_hi:[1,0]
	v_cmp_ne_u32_e64 s[4:5], 1, v110
	s_andn2_b64 vcc, exec, s[44:45]
	ds_write_b128 v119, v[106:109]
	s_cbranch_vccnz .LBB0_659
	s_lshl_b32 s44, s60, 2
	v_mov_b32_e32 v106, s44
	v_mov_b32_e32 v110, v152
	v_mov_b32_e32 v111, v153
	v_pk_mul_f32 v[108:109], v[10:11], v[110:111] op_sel_hi:[1,0]
	v_pk_mul_f32 v[106:107], v[8:9], v[110:111] op_sel_hi:[1,0]
	ds_write_b128 v120, v[106:109]
	v_mov_b32_e32 v106, v111
	s_cbranch_execnz .LBB0_615

.LBB0_615:
	s_waitcnt vmcnt(12)
	v_pk_mul_f32 v[108:109], v[14:15], v[106:107] op_sel_hi:[1,0]
	v_pk_mul_f32 v[106:107], v[12:13], v[106:107] op_sel_hi:[1,0]
	s_and_b64 vcc, exec, s[4:5]
	ds_write_b128 v121, v[106:109]
	s_cbranch_vccnz .LBB0_660
	s_lshl_b32 s44, s60, 2
	v_mov_b32_e32 v106, s44
	v_mov_b32_e32 v110, v154
	v_mov_b32_e32 v111, v155
	v_pk_mul_f32 v[108:109], v[18:19], v[110:111] op_sel_hi:[1,0]
	v_pk_mul_f32 v[106:107], v[16:17], v[110:111] op_sel_hi:[1,0]
	ds_write_b128 v122, v[106:109]
	v_mov_b32_e32 v106, v111
	s_cbranch_execnz .LBB0_618

.LBB0_618:
	s_waitcnt vmcnt(10)
	v_pk_mul_f32 v[108:109], v[22:23], v[106:107] op_sel_hi:[1,0]
	v_pk_mul_f32 v[106:107], v[20:21], v[106:107] op_sel_hi:[1,0]
	s_and_b64 vcc, exec, s[4:5]
	ds_write_b128 v123, v[106:109]
	s_cbranch_vccnz .LBB0_661
	s_lshl_b32 s44, s60, 2
	v_mov_b32_e32 v106, s44
	v_mov_b32_e32 v110, v156
	v_mov_b32_e32 v111, v157
	v_pk_mul_f32 v[108:109], v[26:27], v[110:111] op_sel_hi:[1,0]
	v_pk_mul_f32 v[106:107], v[24:25], v[110:111] op_sel_hi:[1,0]
	ds_write_b128 v124, v[106:109]
	v_mov_b32_e32 v106, v111
	s_cbranch_execnz .LBB0_621

.LBB0_621:
	s_waitcnt vmcnt(8)
	v_pk_mul_f32 v[108:109], v[30:31], v[106:107] op_sel_hi:[1,0]
	v_pk_mul_f32 v[106:107], v[28:29], v[106:107] op_sel_hi:[1,0]
	s_and_b64 vcc, exec, s[4:5]
	ds_write_b128 v125, v[106:109]
	s_cbranch_vccnz .LBB0_662
	s_lshl_b32 s44, s60, 2
	v_mov_b32_e32 v106, s44
	v_mov_b32_e32 v110, v158
	v_mov_b32_e32 v111, v159
	v_pk_mul_f32 v[108:109], v[34:35], v[110:111] op_sel_hi:[1,0]
	v_pk_mul_f32 v[106:107], v[32:33], v[110:111] op_sel_hi:[1,0]
	ds_write_b128 v126, v[106:109]
	v_mov_b32_e32 v106, v111
	s_cbranch_execnz .LBB0_624

.LBB0_624:
	s_waitcnt vmcnt(6)
	v_pk_mul_f32 v[108:109], v[38:39], v[106:107] op_sel_hi:[1,0]
	v_pk_mul_f32 v[106:107], v[36:37], v[106:107] op_sel_hi:[1,0]
	s_and_b64 vcc, exec, s[4:5]
	ds_write_b128 v127, v[106:109]
	s_cbranch_vccnz .LBB0_663
	s_lshl_b32 s44, s60, 2
	v_mov_b32_e32 v106, s44
	v_mov_b32_e32 v110, v160
	v_mov_b32_e32 v111, v161
	v_pk_mul_f32 v[108:109], v[42:43], v[110:111] op_sel_hi:[1,0]
	v_pk_mul_f32 v[106:107], v[40:41], v[110:111] op_sel_hi:[1,0]
	ds_write_b128 v128, v[106:109]
	v_mov_b32_e32 v106, v111
	s_cbranch_execnz .LBB0_627

.LBB0_627:
	s_waitcnt vmcnt(4)
	v_pk_mul_f32 v[108:109], v[46:47], v[106:107] op_sel_hi:[1,0]
	v_pk_mul_f32 v[106:107], v[44:45], v[106:107] op_sel_hi:[1,0]
	s_and_b64 vcc, exec, s[4:5]
	ds_write_b128 v129, v[106:109]
	s_cbranch_vccnz .LBB0_664
	s_lshl_b32 s44, s60, 2
	v_mov_b32_e32 v106, s44
	v_mov_b32_e32 v110, v162
	v_mov_b32_e32 v111, v163
	v_pk_mul_f32 v[108:109], v[50:51], v[110:111] op_sel_hi:[1,0]
	v_pk_mul_f32 v[106:107], v[48:49], v[110:111] op_sel_hi:[1,0]
	ds_write_b128 v130, v[106:109]
	v_mov_b32_e32 v106, v111
	s_cbranch_execnz .LBB0_630

.LBB0_630:
	s_waitcnt vmcnt(2)
	v_pk_mul_f32 v[108:109], v[54:55], v[106:107] op_sel_hi:[1,0]
	v_pk_mul_f32 v[106:107], v[52:53], v[106:107] op_sel_hi:[1,0]
	s_and_b64 vcc, exec, s[4:5]
	ds_write_b128 v131, v[106:109]
	s_cbranch_vccnz .LBB0_665
	s_lshl_b32 s4, s60, 2
	v_mov_b32_e32 v106, s4
	v_mov_b32_e32 v110, v164
	v_mov_b32_e32 v111, v165
	v_pk_mul_f32 v[108:109], v[58:59], v[110:111] op_sel_hi:[1,0]
	v_pk_mul_f32 v[106:107], v[56:57], v[110:111] op_sel_hi:[1,0]
	ds_write_b128 v132, v[106:109]
	v_mov_b32_e32 v106, v111
	s_cbranch_execnz .LBB0_633
